# combo6 + hand-written output-projection epilogue (half tile of residual loads in flight, fma in place, stores behind next loads)
# baseline (speedup 1.0000x reference)
.LBB0_802:
	s_andn2_b64 vcc, exec, s[0:1]
	s_mov_b64 s[0:1], -1
	v_and_b32_e32 v160, 63, v234
	v_lshrrev_b32_e32 v161, 6, v234
	v_and_b32_e32 v162, 15, v160
	v_lshrrev_b32_e32 v160, 4, v160
	v_lshrrev_b32_e32 v163, 2, v161
	v_and_b32_e32 v161, 3, v161
	v_lshl_add_u32 v162, v163, 6, v162
	v_lshlrev_b32_e32 v161, 5, v161
	v_lshl_add_u32 v161, v160, 3, v161
	v_lshlrev_b32_e32 v254, 12, v162
	v_lshl_add_u32 v254, v161, 2, v254
	v_lshlrev_b32_e32 v255, 2, v161
	v_readlane_b32 s56, v253, 25
	v_readlane_b32 s57, v253, 26
	s_lshl_b32 s66, s40, 20
	s_lshl_b32 s67, s54, 10
	s_add_u32 s66, s66, s67
	s_add_u32 s58, s56, s66
	s_addc_u32 s59, s57, 0
	s_add_u32 s60, s20, s66
	s_addc_u32 s61, s21, 0
	s_add_u32 s62, s58, 0x80000
	s_addc_u32 s63, s59, 0
	s_add_u32 s64, s60, 0x80000
	s_addc_u32 s65, s61, 0
	s_lshr_b32 s66, s40, 5
	s_mul_i32 s66, s66, 0x3000
	s_add_u32 s66, s66, s67
	s_add_u32 s66, s66, 0x2000
	s_add_u32 s68, s22, s66
	s_addc_u32 s69, s23, 0
	global_load_dwordx4 v[128:131], v255, s[68:69]
	global_load_dwordx4 v[132:135], v255, s[68:69] offset:16
	global_load_dwordx4 v[136:139], v255, s[68:69] offset:512
	global_load_dwordx4 v[140:143], v255, s[68:69] offset:528
	global_load_dwordx4 v[172:175], v254, s[58:59]
	global_load_dwordx4 v[176:179], v254, s[58:59] offset:16
	global_load_dwordx4 v[180:183], v254, s[58:59] offset:512
	global_load_dwordx4 v[184:187], v254, s[58:59] offset:528
	s_add_u32 s58, s58, 0x10000
	s_addc_u32 s59, s59, 0
	global_load_dwordx4 v[188:191], v254, s[58:59]
	global_load_dwordx4 v[192:195], v254, s[58:59] offset:16
	global_load_dwordx4 v[196:199], v254, s[58:59] offset:512
	global_load_dwordx4 v[200:203], v254, s[58:59] offset:528
	s_add_u32 s58, s58, 0x10000
	s_addc_u32 s59, s59, 0
	global_load_dwordx4 v[204:207], v254, s[58:59]
	global_load_dwordx4 v[208:211], v254, s[58:59] offset:16
	global_load_dwordx4 v[212:215], v254, s[58:59] offset:512
	global_load_dwordx4 v[216:219], v254, s[58:59] offset:528
	s_add_u32 s58, s58, 0x10000
	s_addc_u32 s59, s59, 0
	global_load_dwordx4 v[220:223], v254, s[58:59]
	global_load_dwordx4 v[224:227], v254, s[58:59] offset:16
	global_load_dwordx4 v[228:231], v254, s[58:59] offset:512
	global_load_dwordx4 v[236:239], v254, s[58:59] offset:528
	s_waitcnt vmcnt(14)
	v_fma_f32 v120, v120, v128, v172
	v_fma_f32 v121, v121, v129, v173
	v_fma_f32 v122, v122, v130, v174
	v_fma_f32 v123, v123, v131, v175
	v_fma_f32 v124, v124, v132, v176
	v_fma_f32 v125, v125, v133, v177
	v_fma_f32 v126, v126, v134, v178
	v_fma_f32 v127, v127, v135, v179
	global_load_dwordx4 v[172:175], v254, s[62:63]
	global_load_dwordx4 v[176:179], v254, s[62:63] offset:16
	global_store_dwordx4 v254, v[120:123], s[60:61]
	global_store_dwordx4 v254, v[124:127], s[60:61] offset:16
	s_waitcnt vmcnt(16)
	v_fma_f32 v108, v108, v136, v180
	v_fma_f32 v109, v109, v137, v181
	v_fma_f32 v110, v110, v138, v182
	v_fma_f32 v111, v111, v139, v183
	v_fma_f32 v100, v100, v140, v184
	v_fma_f32 v101, v101, v141, v185
	v_fma_f32 v102, v102, v142, v186
	v_fma_f32 v103, v103, v143, v187
	global_load_dwordx4 v[180:183], v254, s[62:63] offset:512
	global_load_dwordx4 v[184:187], v254, s[62:63] offset:528
	s_add_u32 s62, s62, 0x10000
	s_addc_u32 s63, s63, 0
	global_store_dwordx4 v254, v[108:111], s[60:61] offset:512
	global_store_dwordx4 v254, v[100:103], s[60:61] offset:528
	s_add_u32 s60, s60, 0x10000
	s_addc_u32 s61, s61, 0
	s_waitcnt vmcnt(18)
	v_fma_f32 v112, v112, v128, v188
	v_fma_f32 v113, v113, v129, v189
	v_fma_f32 v114, v114, v130, v190
	v_fma_f32 v115, v115, v131, v191
	v_fma_f32 v116, v116, v132, v192
	v_fma_f32 v117, v117, v133, v193
	v_fma_f32 v118, v118, v134, v194
	v_fma_f32 v119, v119, v135, v195
	global_load_dwordx4 v[188:191], v254, s[62:63]
	global_load_dwordx4 v[192:195], v254, s[62:63] offset:16
	global_store_dwordx4 v254, v[112:115], s[60:61]
	global_store_dwordx4 v254, v[116:119], s[60:61] offset:16
	s_waitcnt vmcnt(20)
	v_fma_f32 v104, v104, v136, v196
	v_fma_f32 v105, v105, v137, v197
	v_fma_f32 v106, v106, v138, v198
	v_fma_f32 v107, v107, v139, v199
	v_fma_f32 v96, v96, v140, v200
	v_fma_f32 v97, v97, v141, v201
	v_fma_f32 v98, v98, v142, v202
	v_fma_f32 v99, v99, v143, v203
	global_load_dwordx4 v[196:199], v254, s[62:63] offset:512
	global_load_dwordx4 v[200:203], v254, s[62:63] offset:528
	s_add_u32 s62, s62, 0x10000
	s_addc_u32 s63, s63, 0
	global_store_dwordx4 v254, v[104:107], s[60:61] offset:512
	global_store_dwordx4 v254, v[96:99], s[60:61] offset:528
	s_add_u32 s60, s60, 0x10000
	s_addc_u32 s61, s61, 0
	s_waitcnt vmcnt(22)
	v_fma_f32 v92, v92, v128, v204
	v_fma_f32 v93, v93, v129, v205
	v_fma_f32 v94, v94, v130, v206
	v_fma_f32 v95, v95, v131, v207
	v_fma_f32 v88, v88, v132, v208
	v_fma_f32 v89, v89, v133, v209
	v_fma_f32 v90, v90, v134, v210
	v_fma_f32 v91, v91, v135, v211
	global_load_dwordx4 v[204:207], v254, s[62:63]
	global_load_dwordx4 v[208:211], v254, s[62:63] offset:16
	global_store_dwordx4 v254, v[92:95], s[60:61]
	global_store_dwordx4 v254, v[88:91], s[60:61] offset:16
	s_waitcnt vmcnt(24)
	v_fma_f32 v76, v76, v136, v212
	v_fma_f32 v77, v77, v137, v213
	v_fma_f32 v78, v78, v138, v214
	v_fma_f32 v79, v79, v139, v215
	v_fma_f32 v72, v72, v140, v216
	v_fma_f32 v73, v73, v141, v217
	v_fma_f32 v74, v74, v142, v218
	v_fma_f32 v75, v75, v143, v219
	global_load_dwordx4 v[212:215], v254, s[62:63] offset:512
	global_load_dwordx4 v[216:219], v254, s[62:63] offset:528
	s_add_u32 s62, s62, 0x10000
	s_addc_u32 s63, s63, 0
	global_store_dwordx4 v254, v[76:79], s[60:61] offset:512
	global_store_dwordx4 v254, v[72:75], s[60:61] offset:528
	s_add_u32 s60, s60, 0x10000
	s_addc_u32 s61, s61, 0
	s_waitcnt vmcnt(26)
	v_fma_f32 v84, v84, v128, v220
	v_fma_f32 v85, v85, v129, v221
	v_fma_f32 v86, v86, v130, v222
	v_fma_f32 v87, v87, v131, v223
	v_fma_f32 v80, v80, v132, v224
	v_fma_f32 v81, v81, v133, v225
	v_fma_f32 v82, v82, v134, v226
	v_fma_f32 v83, v83, v135, v227
	global_load_dwordx4 v[220:223], v254, s[62:63]
	global_load_dwordx4 v[224:227], v254, s[62:63] offset:16
	global_store_dwordx4 v254, v[84:87], s[60:61]
	global_store_dwordx4 v254, v[80:83], s[60:61] offset:16
	s_waitcnt vmcnt(28)
	v_fma_f32 v68, v68, v136, v228
	v_fma_f32 v69, v69, v137, v229
	v_fma_f32 v70, v70, v138, v230
	v_fma_f32 v71, v71, v139, v231
	v_fma_f32 v64, v64, v140, v236
	v_fma_f32 v65, v65, v141, v237
	v_fma_f32 v66, v66, v142, v238
	v_fma_f32 v67, v67, v143, v239
	global_load_dwordx4 v[228:231], v254, s[62:63] offset:512
	global_load_dwordx4 v[236:239], v254, s[62:63] offset:528
	global_store_dwordx4 v254, v[68:71], s[60:61] offset:512
	global_store_dwordx4 v254, v[64:67], s[60:61] offset:528
	s_waitcnt vmcnt(30)
	v_fma_f32 v60, v60, v128, v172
	v_fma_f32 v61, v61, v129, v173
	v_fma_f32 v62, v62, v130, v174
	v_fma_f32 v63, v63, v131, v175
	v_fma_f32 v56, v56, v132, v176
	v_fma_f32 v57, v57, v133, v177
	v_fma_f32 v58, v58, v134, v178
	v_fma_f32 v59, v59, v135, v179
	global_store_dwordx4 v254, v[60:63], s[64:65]
	global_store_dwordx4 v254, v[56:59], s[64:65] offset:16
	s_waitcnt vmcnt(28)
	v_fma_f32 v44, v44, v136, v180
	v_fma_f32 v45, v45, v137, v181
	v_fma_f32 v46, v46, v138, v182
	v_fma_f32 v47, v47, v139, v183
	v_fma_f32 v40, v40, v140, v184
	v_fma_f32 v41, v41, v141, v185
	v_fma_f32 v42, v42, v142, v186
	v_fma_f32 v43, v43, v143, v187
	global_store_dwordx4 v254, v[44:47], s[64:65] offset:512
	global_store_dwordx4 v254, v[40:43], s[64:65] offset:528
	s_add_u32 s64, s64, 0x10000
	s_addc_u32 s65, s65, 0
	s_waitcnt vmcnt(26)
	v_fma_f32 v52, v52, v128, v188
	v_fma_f32 v53, v53, v129, v189
	v_fma_f32 v54, v54, v130, v190
	v_fma_f32 v55, v55, v131, v191
	v_fma_f32 v48, v48, v132, v192
	v_fma_f32 v49, v49, v133, v193
	v_fma_f32 v50, v50, v134, v194
	v_fma_f32 v51, v51, v135, v195
	global_store_dwordx4 v254, v[52:55], s[64:65]
	global_store_dwordx4 v254, v[48:51], s[64:65] offset:16
	s_waitcnt vmcnt(24)
	v_fma_f32 v36, v36, v136, v196
	v_fma_f32 v37, v37, v137, v197
	v_fma_f32 v38, v38, v138, v198
	v_fma_f32 v39, v39, v139, v199
	v_fma_f32 v32, v32, v140, v200
	v_fma_f32 v33, v33, v141, v201
	v_fma_f32 v34, v34, v142, v202
	v_fma_f32 v35, v35, v143, v203
	global_store_dwordx4 v254, v[36:39], s[64:65] offset:512
	global_store_dwordx4 v254, v[32:35], s[64:65] offset:528
	s_add_u32 s64, s64, 0x10000
	s_addc_u32 s65, s65, 0
	s_waitcnt vmcnt(22)
	v_fma_f32 v28, v28, v128, v204
	v_fma_f32 v29, v29, v129, v205
	v_fma_f32 v30, v30, v130, v206
	v_fma_f32 v31, v31, v131, v207
	v_fma_f32 v24, v24, v132, v208
	v_fma_f32 v25, v25, v133, v209
	v_fma_f32 v26, v26, v134, v210
	v_fma_f32 v27, v27, v135, v211
	global_store_dwordx4 v254, v[28:31], s[64:65]
	global_store_dwordx4 v254, v[24:27], s[64:65] offset:16
	s_waitcnt vmcnt(20)
	v_fma_f32 v12, v12, v136, v212
	v_fma_f32 v13, v13, v137, v213
	v_fma_f32 v14, v14, v138, v214
	v_fma_f32 v15, v15, v139, v215
	v_fma_f32 v8, v8, v140, v216
	v_fma_f32 v9, v9, v141, v217
	v_fma_f32 v10, v10, v142, v218
	v_fma_f32 v11, v11, v143, v219
	global_store_dwordx4 v254, v[12:15], s[64:65] offset:512
	global_store_dwordx4 v254, v[8:11], s[64:65] offset:528
	s_add_u32 s64, s64, 0x10000
	s_addc_u32 s65, s65, 0
	s_waitcnt vmcnt(18)
	v_fma_f32 v20, v20, v128, v220
	v_fma_f32 v21, v21, v129, v221
	v_fma_f32 v22, v22, v130, v222
	v_fma_f32 v23, v23, v131, v223
	v_fma_f32 v16, v16, v132, v224
	v_fma_f32 v17, v17, v133, v225
	v_fma_f32 v18, v18, v134, v226
	v_fma_f32 v19, v19, v135, v227
	global_store_dwordx4 v254, v[20:23], s[64:65]
	global_store_dwordx4 v254, v[16:19], s[64:65] offset:16
	s_waitcnt vmcnt(16)
	v_fma_f32 v4, v4, v136, v228
	v_fma_f32 v5, v5, v137, v229
	v_fma_f32 v6, v6, v138, v230
	v_fma_f32 v7, v7, v139, v231
	v_fma_f32 v0, v0, v140, v236
	v_fma_f32 v1, v1, v141, v237
	v_fma_f32 v2, v2, v142, v238
	v_fma_f32 v3, v3, v143, v239
	global_store_dwordx4 v254, v[4:7], s[64:65] offset:512
	global_store_dwordx4 v254, v[0:3], s[64:65] offset:528
	s_cbranch_vccnz .LBB0_791
	s_andn2_b64 vcc, exec, s[8:9]
	s_cbranch_vccnz .LBB0_790
	s_barrier
	s_branch .LBB0_790
